# attention loops: fmaxf-canonicalizing row-max tree (54 VALU) replaced by a 16-op v_max3 tree
# speedup vs baseline: 1.0057x; 1.0057x over previous
.LBB0_340:
	v_add_u32_e32 v101, s4, v96
	s_waitcnt vmcnt(0)
	ds_read_b128 v[34:37], v101
	v_add_u32_e32 v100, s4, v95
	ds_read_b128 v[104:107], v100
	ds_read_b128 v[50:53], v101 offset:4096
	v_add_u32_e32 v99, s4, v94
	v_add_u32_e32 v98, s4, v93
	s_waitcnt lgkmcnt(0)
	v_mfma_f32_32x32x16_bf16 v[34:49], v[34:37], v[66:69], 0
	v_mfma_f32_32x32x16_bf16 v[34:49], v[104:107], v[70:73], v[34:49]
	ds_read_b128 v[104:107], v100 offset:4096
	v_mfma_f32_32x32x16_bf16 v[50:65], v[50:53], v[66:69], 0
	s_waitcnt lgkmcnt(0)
	v_mfma_f32_32x32x16_bf16 v[50:65], v[104:107], v[70:73], v[50:65]
	ds_read_b128 v[104:107], v99
	s_waitcnt lgkmcnt(0)
	v_mfma_f32_32x32x16_bf16 v[34:49], v[104:107], v[74:77], v[34:49]
	ds_read_b128 v[104:107], v99 offset:4096
	s_waitcnt lgkmcnt(0)
	v_mfma_f32_32x32x16_bf16 v[50:65], v[104:107], v[74:77], v[50:65]
	ds_read_b128 v[104:107], v98 offset:4096
	s_waitcnt lgkmcnt(0)
	v_mfma_f32_32x32x16_bf16 v[50:65], v[104:107], v[78:81], v[50:65]
	ds_read_b128 v[104:107], v98
	s_waitcnt lgkmcnt(0)
	v_mfma_f32_32x32x16_bf16 v[34:49], v[104:107], v[78:81], v[34:49]
	s_nop 8
	v_max3_f32 v0, v50, v51, v52
	v_max3_f32 v0, v0, v53, v54
	v_max3_f32 v0, v0, v55, v56
	v_max3_f32 v0, v0, v57, v58
	v_max3_f32 v0, v0, v59, v60
	v_max3_f32 v0, v0, v61, v62
	v_max3_f32 v0, v0, v63, v64
	v_max3_f32 v97, v34, v35, v36
	v_max3_f32 v97, v97, v37, v38
	v_max3_f32 v97, v97, v39, v40
	v_max3_f32 v97, v97, v41, v42
	v_max3_f32 v97, v97, v43, v44
	v_max3_f32 v97, v97, v45, v46
	v_max3_f32 v97, v97, v47, v48
	v_max3_f32 v97, v97, v49, v65
	v_max_f32_e32 v0, v0, v97
	v_and_b32_e32 v104, 64, v221
	v_xor_b32_e32 v97, 32, v221
	v_add_u32_e32 v104, 64, v104
	v_cmp_lt_i32_e32 vcc, v97, v104
	s_nop 1
	v_cndmask_b32_e32 v97, v221, v97, vcc
	v_lshlrev_b32_e32 v104, 2, v97
	ds_bpermute_b32 v97, v104, v0
	s_waitcnt lgkmcnt(0)
	v_max3_f32 v97, v103, v0, v97
	v_sub_f32_e32 v0, v34, v97
	v_exp_f32_e32 v34, v0
	v_sub_f32_e32 v0, v50, v97
	v_exp_f32_e32 v50, v0
	v_sub_f32_e32 v0, v35, v97
	v_exp_f32_e32 v35, v0
	v_sub_f32_e32 v0, v51, v97
	v_exp_f32_e32 v51, v0
	v_sub_f32_e32 v36, v36, v97
	v_sub_f32_e32 v52, v52, v97
	v_exp_f32_e32 v36, v36
	v_exp_f32_e32 v52, v52
	v_sub_f32_e32 v0, v103, v97
	v_add_f32_e32 v103, v34, v50
	v_add_f32_e32 v103, 0, v103
	v_add_f32_e32 v105, v35, v51
	v_add_f32_e32 v103, v105, v103
	v_add_f32_e32 v105, v36, v52
	v_sub_f32_e32 v38, v38, v97
	v_sub_f32_e32 v37, v37, v97
	v_sub_f32_e32 v53, v53, v97
	v_add_f32_e32 v105, v105, v103
	v_exp_f32_e32 v103, v38
	v_sub_f32_e32 v38, v54, v97
	v_exp_f32_e32 v37, v37
	v_exp_f32_e32 v53, v53
	v_exp_f32_e32 v54, v38
	v_sub_f32_e32 v38, v39, v97
	v_exp_f32_e32 v39, v38
	v_sub_f32_e32 v38, v55, v97
	v_exp_f32_e32 v55, v38
	v_sub_f32_e32 v40, v40, v97
	v_sub_f32_e32 v56, v56, v97
	v_exp_f32_e32 v40, v40
	v_exp_f32_e32 v56, v56
	v_sub_f32_e32 v41, v41, v97
	v_sub_f32_e32 v57, v57, v97
	v_add_f32_e32 v106, v37, v53
	v_exp_f32_e32 v41, v41
	v_exp_f32_e32 v57, v57
	v_sub_f32_e32 v42, v42, v97
	v_sub_f32_e32 v58, v58, v97
	v_add_f32_e32 v38, v106, v105
	v_add_f32_e32 v105, v103, v54
	v_exp_f32_e32 v42, v42
	v_exp_f32_e32 v58, v58
	v_sub_f32_e32 v43, v43, v97
	v_sub_f32_e32 v59, v59, v97
	v_add_f32_e32 v38, v105, v38
	v_add_f32_e32 v105, v39, v55
	v_exp_f32_e32 v43, v43
	v_exp_f32_e32 v59, v59
	v_sub_f32_e32 v44, v44, v97
	v_sub_f32_e32 v60, v60, v97
	v_add_f32_e32 v38, v105, v38
	v_add_f32_e32 v105, v40, v56
	v_exp_f32_e32 v44, v44
	v_exp_f32_e32 v60, v60
	v_sub_f32_e32 v45, v45, v97
	v_sub_f32_e32 v61, v61, v97
	v_add_f32_e32 v38, v105, v38
	v_add_f32_e32 v105, v41, v57
	v_exp_f32_e32 v45, v45
	v_exp_f32_e32 v61, v61
	v_sub_f32_e32 v46, v46, v97
	v_sub_f32_e32 v62, v62, v97
	v_add_f32_e32 v38, v105, v38
	v_add_f32_e32 v105, v42, v58
	v_exp_f32_e32 v46, v46
	v_exp_f32_e32 v62, v62
	v_sub_f32_e32 v47, v47, v97
	v_sub_f32_e32 v63, v63, v97
	v_add_f32_e32 v38, v105, v38
	v_add_f32_e32 v105, v43, v59
	v_exp_f32_e32 v47, v47
	v_exp_f32_e32 v63, v63
	v_sub_f32_e32 v48, v48, v97
	v_sub_f32_e32 v64, v64, v97
	v_add_f32_e32 v38, v105, v38
	v_add_f32_e32 v105, v44, v60
	v_exp_f32_e32 v48, v48
	v_exp_f32_e32 v64, v64
	v_sub_f32_e32 v49, v49, v97
	v_sub_f32_e32 v65, v65, v97
	v_add_f32_e32 v38, v105, v38
	v_add_f32_e32 v105, v45, v61
	v_exp_f32_e32 v49, v49
	v_exp_f32_e32 v65, v65
	v_add_f32_e32 v38, v105, v38
	v_add_f32_e32 v105, v46, v62
	v_add_f32_e32 v38, v105, v38
	v_add_f32_e32 v105, v47, v63
	v_add_f32_e32 v38, v105, v38
	v_add_f32_e32 v105, v48, v64
	v_add_f32_e32 v38, v105, v38
	v_add_f32_e32 v105, v49, v65
	v_add_f32_e32 v38, v105, v38
	v_exp_f32_e32 v0, v0
	ds_bpermute_b32 v104, v104, v38
	v_cmp_neq_f32_e32 vcc, 1.0, v0
	s_cbranch_vccz .LBB0_342
	v_pk_mul_f32 v[32:33], v[32:33], v[0:1] op_sel_hi:[1,0]
	v_pk_mul_f32 v[30:31], v[30:31], v[0:1] op_sel_hi:[1,0]
	v_pk_mul_f32 v[28:29], v[28:29], v[0:1] op_sel_hi:[1,0]
	v_pk_mul_f32 v[26:27], v[26:27], v[0:1] op_sel_hi:[1,0]
	v_pk_mul_f32 v[24:25], v[24:25], v[0:1] op_sel_hi:[1,0]
	v_pk_mul_f32 v[22:23], v[22:23], v[0:1] op_sel_hi:[1,0]
	v_pk_mul_f32 v[20:21], v[20:21], v[0:1] op_sel_hi:[1,0]
	v_pk_mul_f32 v[18:19], v[18:19], v[0:1] op_sel_hi:[1,0]
	v_pk_mul_f32 v[16:17], v[16:17], v[0:1] op_sel_hi:[1,0]
	v_pk_mul_f32 v[14:15], v[14:15], v[0:1] op_sel_hi:[1,0]
	v_pk_mul_f32 v[12:13], v[12:13], v[0:1] op_sel_hi:[1,0]
	v_pk_mul_f32 v[10:11], v[10:11], v[0:1] op_sel_hi:[1,0]
	v_pk_mul_f32 v[8:9], v[8:9], v[0:1] op_sel_hi:[1,0]
	v_pk_mul_f32 v[6:7], v[6:7], v[0:1] op_sel_hi:[1,0]
	v_pk_mul_f32 v[4:5], v[4:5], v[0:1] op_sel_hi:[1,0]
	v_pk_mul_f32 v[2:3], v[2:3], v[0:1] op_sel_hi:[1,0]

.LBB0_352:
	s_mul_i32 s0, s5, 0xa000
	v_add_u32_e32 v185, s0, v176
	s_waitcnt vmcnt(0)
	ds_read_b128 v[66:69], v185
	ds_read_b128 v[82:85], v185 offset:12288
	v_add_u32_e32 v187, s0, v178
	ds_read_b128 v[188:191], v187
	v_add_u32_e32 v192, s0, v180
	v_add_u32_e32 v193, s0, v182
	s_waitcnt lgkmcnt(0)
	v_mfma_f32_32x32x16_bf16 v[66:81], v[66:69], v[98:101], 0
	v_mfma_f32_32x32x16_bf16 v[66:81], v[188:191], v[102:105], v[66:81]
	ds_read_b128 v[188:191], v187 offset:12288
	v_mfma_f32_32x32x16_bf16 v[82:97], v[82:85], v[98:101], 0
	s_waitcnt lgkmcnt(0)
	v_mfma_f32_32x32x16_bf16 v[82:97], v[188:191], v[102:105], v[82:97]
	ds_read_b128 v[188:191], v192
	s_waitcnt lgkmcnt(0)
	v_mfma_f32_32x32x16_bf16 v[66:81], v[188:191], v[106:109], v[66:81]
	ds_read_b128 v[188:191], v192 offset:12288
	s_waitcnt lgkmcnt(0)
	v_mfma_f32_32x32x16_bf16 v[82:97], v[188:191], v[106:109], v[82:97]
	ds_read_b128 v[188:191], v193
	s_waitcnt lgkmcnt(0)
	v_mfma_f32_32x32x16_bf16 v[66:81], v[188:191], v[110:113], v[66:81]
	ds_read_b128 v[188:191], v193 offset:12288
	s_waitcnt lgkmcnt(0)
	v_mfma_f32_32x32x16_bf16 v[82:97], v[188:191], v[110:113], v[82:97]
	ds_read_b128 v[188:191], v185 offset:128
	s_waitcnt lgkmcnt(0)
	v_mfma_f32_32x32x16_bf16 v[66:81], v[188:191], v[114:117], v[66:81]
	ds_read_b128 v[188:191], v185 offset:12416
	s_waitcnt lgkmcnt(0)
	v_mfma_f32_32x32x16_bf16 v[82:97], v[188:191], v[114:117], v[82:97]
	ds_read_b128 v[188:191], v187 offset:128
	s_waitcnt lgkmcnt(0)
	v_mfma_f32_32x32x16_bf16 v[66:81], v[188:191], v[118:121], v[66:81]
	ds_read_b128 v[188:191], v187 offset:12416
	s_waitcnt lgkmcnt(0)
	v_mfma_f32_32x32x16_bf16 v[82:97], v[188:191], v[118:121], v[82:97]
	ds_read_b128 v[188:191], v192 offset:128
	s_waitcnt lgkmcnt(0)
	v_mfma_f32_32x32x16_bf16 v[66:81], v[188:191], v[122:125], v[66:81]
	ds_read_b128 v[188:191], v192 offset:12416
	s_waitcnt lgkmcnt(0)
	v_mfma_f32_32x32x16_bf16 v[82:97], v[188:191], v[122:125], v[82:97]
	ds_read_b128 v[188:191], v193 offset:128
	s_waitcnt lgkmcnt(0)
	v_mfma_f32_32x32x16_bf16 v[66:81], v[188:191], v[126:129], v[66:81]
	ds_read_b128 v[188:191], v193 offset:12416
	s_waitcnt lgkmcnt(0)
	v_mfma_f32_32x32x16_bf16 v[82:97], v[188:191], v[126:129], v[82:97]
	ds_read_b128 v[188:191], v185 offset:256
	s_waitcnt lgkmcnt(0)
	v_mfma_f32_32x32x16_bf16 v[66:81], v[188:191], v[130:133], v[66:81]
	ds_read_b128 v[188:191], v185 offset:12544
	s_waitcnt lgkmcnt(0)
	v_mfma_f32_32x32x16_bf16 v[82:97], v[188:191], v[130:133], v[82:97]
	ds_read_b128 v[188:191], v187 offset:256
	s_waitcnt lgkmcnt(0)
	v_mfma_f32_32x32x16_bf16 v[66:81], v[188:191], v[134:137], v[66:81]
	ds_read_b128 v[188:191], v187 offset:12544
	s_waitcnt lgkmcnt(0)
	v_mfma_f32_32x32x16_bf16 v[82:97], v[188:191], v[134:137], v[82:97]
	ds_read_b128 v[188:191], v192 offset:256
	s_waitcnt lgkmcnt(0)
	v_mfma_f32_32x32x16_bf16 v[66:81], v[188:191], v[138:141], v[66:81]
	ds_read_b128 v[188:191], v192 offset:12544
	s_waitcnt lgkmcnt(0)
	v_mfma_f32_32x32x16_bf16 v[82:97], v[188:191], v[138:141], v[82:97]
	ds_read_b128 v[188:191], v193 offset:12544
	s_waitcnt lgkmcnt(0)
	v_mfma_f32_32x32x16_bf16 v[82:97], v[188:191], v[142:145], v[82:97]
	ds_read_b128 v[188:191], v193 offset:256
	s_waitcnt lgkmcnt(0)
	v_mfma_f32_32x32x16_bf16 v[66:81], v[188:191], v[142:145], v[66:81]
	s_nop 8
	v_max3_f32 v185, v82, v83, v84
	v_max3_f32 v185, v185, v85, v86
	v_max3_f32 v185, v185, v87, v88
	v_max3_f32 v185, v185, v89, v90
	v_max3_f32 v185, v185, v91, v92
	v_max3_f32 v185, v185, v93, v94
	v_max3_f32 v185, v185, v95, v96
	v_max3_f32 v187, v66, v67, v68
	v_max3_f32 v187, v187, v69, v70
	v_max3_f32 v187, v187, v71, v72
	v_max3_f32 v187, v187, v73, v74
	v_max3_f32 v187, v187, v75, v76
	v_max3_f32 v187, v187, v77, v78
	v_max3_f32 v187, v187, v79, v80
	v_max3_f32 v187, v187, v81, v97
	v_max_f32_e32 v185, v185, v187
	v_and_b32_e32 v188, 64, v221
	v_xor_b32_e32 v187, 32, v221
	v_add_u32_e32 v188, 64, v188
	v_cmp_lt_i32_e32 vcc, v187, v188
	s_nop 1
	v_cndmask_b32_e32 v187, v221, v187, vcc
	v_lshlrev_b32_e32 v193, 2, v187
	ds_bpermute_b32 v187, v193, v185
	s_waitcnt lgkmcnt(0)
	v_max3_f32 v185, v186, v185, v187
	v_sub_f32_e32 v66, v66, v185
	v_exp_f32_e32 v187, v66
	v_sub_f32_e32 v66, v82, v185
	v_exp_f32_e32 v188, v66
	v_sub_f32_e32 v66, v67, v185
	v_exp_f32_e32 v67, v66
	v_sub_f32_e32 v66, v83, v185
	v_exp_f32_e32 v83, v66
	v_sub_f32_e32 v68, v68, v185
	v_sub_f32_e32 v84, v84, v185
	v_exp_f32_e32 v68, v68
	v_exp_f32_e32 v84, v84
	v_add_f32_e32 v82, v187, v188
	v_sub_f32_e32 v69, v69, v185
	v_sub_f32_e32 v85, v85, v185
	v_sub_f32_e32 v66, v186, v185
	v_add_f32_e32 v82, 0, v82
	v_add_f32_e32 v186, v67, v83
	v_exp_f32_e32 v69, v69
	v_exp_f32_e32 v85, v85
	v_add_f32_e32 v82, v186, v82
	v_add_f32_e32 v186, v68, v84
	v_sub_f32_e32 v70, v70, v185
	v_add_f32_e32 v82, v186, v82
	v_exp_f32_e32 v186, v70
	v_sub_f32_e32 v70, v86, v185
	v_exp_f32_e32 v86, v70
	v_sub_f32_e32 v70, v71, v185
	v_add_f32_e32 v190, v69, v85
	v_exp_f32_e32 v189, v70
	v_sub_f32_e32 v70, v87, v185
	v_sub_f32_e32 v72, v72, v185
	v_exp_f32_e32 v87, v70
	v_add_f32_e32 v70, v190, v82
	v_exp_f32_e32 v190, v72
	v_sub_f32_e32 v72, v88, v185
	v_exp_f32_e32 v88, v72
	v_add_f32_e32 v71, v186, v86
	v_add_f32_e32 v70, v71, v70
	v_add_f32_e32 v71, v189, v87
	v_sub_f32_e32 v72, v73, v185
	v_exp_f32_e32 v73, v72
	v_sub_f32_e32 v72, v89, v185
	v_add_f32_e32 v70, v71, v70
	v_add_f32_e32 v71, v190, v88
	v_exp_f32_e32 v89, v72
	v_add_f32_e32 v82, v71, v70
	v_sub_f32_e32 v70, v74, v185
	v_sub_f32_e32 v71, v90, v185
	v_exp_f32_e32 v70, v70
	v_exp_f32_e32 v71, v71
	v_sub_f32_e32 v72, v75, v185
	v_sub_f32_e32 v74, v91, v185
	v_exp_f32_e32 v72, v72
	v_exp_f32_e32 v75, v74
	v_sub_f32_e32 v76, v76, v185
	v_sub_f32_e32 v90, v92, v185
	v_sub_f32_e32 v78, v78, v185
	v_exp_f32_e32 v76, v76
	v_exp_f32_e32 v90, v90
	v_sub_f32_e32 v77, v77, v185
	v_sub_f32_e32 v91, v93, v185
	v_exp_f32_e32 v92, v78
	v_sub_f32_e32 v78, v94, v185
	v_add_f32_e32 v191, v73, v89
	v_exp_f32_e32 v77, v77
	v_exp_f32_e32 v91, v91
	v_exp_f32_e32 v93, v78
	v_sub_f32_e32 v78, v79, v185
	v_sub_f32_e32 v79, v80, v185
	v_add_f32_e32 v74, v191, v82
	v_add_f32_e32 v82, v70, v71
	v_exp_f32_e32 v94, v78
	v_sub_f32_e32 v78, v95, v185
	v_exp_f32_e32 v191, v79
	v_sub_f32_e32 v79, v96, v185
	v_add_f32_e32 v74, v82, v74
	v_add_f32_e32 v82, v72, v75
	v_exp_f32_e32 v95, v78
	v_exp_f32_e32 v96, v79
	v_sub_f32_e32 v79, v81, v185
	v_add_f32_e32 v74, v82, v74
	v_add_f32_e32 v82, v76, v90
	v_exp_f32_e32 v192, v79
	v_sub_f32_e32 v79, v97, v185
	v_add_f32_e32 v74, v82, v74
	v_add_f32_e32 v82, v77, v91
	v_exp_f32_e32 v97, v79
	v_add_f32_e32 v74, v82, v74
	v_add_f32_e32 v78, v92, v93
	v_add_f32_e32 v74, v78, v74
	v_add_f32_e32 v78, v94, v95
	v_add_f32_e32 v74, v78, v74
	v_add_f32_e32 v78, v191, v96
	v_add_f32_e32 v74, v78, v74
	v_add_f32_e32 v78, v192, v97
	v_add_f32_e32 v74, v78, v74
	v_exp_f32_e32 v66, v66
	ds_bpermute_b32 v78, v193, v74
	v_cmp_neq_f32_e32 vcc, 1.0, v66
	s_cbranch_vccz .LBB0_354
	v_pk_mul_f32 v[64:65], v[64:65], v[66:67] op_sel_hi:[1,0]
	v_pk_mul_f32 v[62:63], v[62:63], v[66:67] op_sel_hi:[1,0]
	v_pk_mul_f32 v[60:61], v[60:61], v[66:67] op_sel_hi:[1,0]
	v_pk_mul_f32 v[58:59], v[58:59], v[66:67] op_sel_hi:[1,0]
	v_pk_mul_f32 v[56:57], v[56:57], v[66:67] op_sel_hi:[1,0]
	v_pk_mul_f32 v[54:55], v[54:55], v[66:67] op_sel_hi:[1,0]
	v_pk_mul_f32 v[52:53], v[52:53], v[66:67] op_sel_hi:[1,0]
	v_pk_mul_f32 v[50:51], v[50:51], v[66:67] op_sel_hi:[1,0]
	v_pk_mul_f32 v[48:49], v[48:49], v[66:67] op_sel_hi:[1,0]
	v_pk_mul_f32 v[46:47], v[46:47], v[66:67] op_sel_hi:[1,0]
	v_pk_mul_f32 v[44:45], v[44:45], v[66:67] op_sel_hi:[1,0]
	v_pk_mul_f32 v[42:43], v[42:43], v[66:67] op_sel_hi:[1,0]
	v_pk_mul_f32 v[40:41], v[40:41], v[66:67] op_sel_hi:[1,0]
	v_pk_mul_f32 v[38:39], v[38:39], v[66:67] op_sel_hi:[1,0]
	v_pk_mul_f32 v[36:37], v[36:37], v[66:67] op_sel_hi:[1,0]
	v_pk_mul_f32 v[34:35], v[34:35], v[66:67] op_sel_hi:[1,0]
	v_pk_mul_f32 v[32:33], v[32:33], v[66:67] op_sel_hi:[1,0]
	v_pk_mul_f32 v[30:31], v[30:31], v[66:67] op_sel_hi:[1,0]
	v_pk_mul_f32 v[28:29], v[28:29], v[66:67] op_sel_hi:[1,0]
	v_pk_mul_f32 v[26:27], v[26:27], v[66:67] op_sel_hi:[1,0]
	v_pk_mul_f32 v[24:25], v[24:25], v[66:67] op_sel_hi:[1,0]
	v_pk_mul_f32 v[22:23], v[22:23], v[66:67] op_sel_hi:[1,0]
	v_pk_mul_f32 v[20:21], v[20:21], v[66:67] op_sel_hi:[1,0]
	v_pk_mul_f32 v[18:19], v[18:19], v[66:67] op_sel_hi:[1,0]
	v_pk_mul_f32 v[16:17], v[16:17], v[66:67] op_sel_hi:[1,0]
	v_pk_mul_f32 v[14:15], v[14:15], v[66:67] op_sel_hi:[1,0]
	v_pk_mul_f32 v[12:13], v[12:13], v[66:67] op_sel_hi:[1,0]
	v_pk_mul_f32 v[10:11], v[10:11], v[66:67] op_sel_hi:[1,0]
	v_pk_mul_f32 v[8:9], v[8:9], v[66:67] op_sel_hi:[1,0]
	v_pk_mul_f32 v[6:7], v[6:7], v[66:67] op_sel_hi:[1,0]
	v_pk_mul_f32 v[4:5], v[4:5], v[66:67] op_sel_hi:[1,0]
	v_pk_mul_f32 v[2:3], v[2:3], v[66:67] op_sel_hi:[1,0]

.LBB0_369:
	v_add_u32_e32 v99, s4, v94
	s_waitcnt vmcnt(0)
	ds_read_b128 v[34:37], v99
	v_add_u32_e32 v98, s4, v93
	ds_read_b128 v[102:105], v98
	ds_read_b128 v[50:53], v99 offset:4096
	v_add_u32_e32 v97, s4, v92
	v_add_u32_e32 v95, s4, v91
	s_waitcnt lgkmcnt(0)
	v_mfma_f32_32x32x16_bf16 v[34:49], v[34:37], v[66:69], 0
	v_mfma_f32_32x32x16_bf16 v[34:49], v[102:105], v[70:73], v[34:49]
	ds_read_b128 v[102:105], v98 offset:4096
	v_mfma_f32_32x32x16_bf16 v[50:65], v[50:53], v[66:69], 0
	s_waitcnt lgkmcnt(0)
	v_mfma_f32_32x32x16_bf16 v[50:65], v[102:105], v[70:73], v[50:65]
	ds_read_b128 v[102:105], v97
	s_waitcnt lgkmcnt(0)
	v_mfma_f32_32x32x16_bf16 v[34:49], v[102:105], v[74:77], v[34:49]
	ds_read_b128 v[102:105], v97 offset:4096
	s_waitcnt lgkmcnt(0)
	v_mfma_f32_32x32x16_bf16 v[50:65], v[102:105], v[74:77], v[50:65]
	ds_read_b128 v[102:105], v95 offset:4096
	s_waitcnt lgkmcnt(0)
	v_mfma_f32_32x32x16_bf16 v[50:65], v[102:105], v[78:81], v[50:65]
	ds_read_b128 v[102:105], v95
	s_waitcnt lgkmcnt(0)
	v_mfma_f32_32x32x16_bf16 v[34:49], v[102:105], v[78:81], v[34:49]
	s_nop 8
	v_max3_f32 v0, v50, v51, v52
	v_max3_f32 v0, v0, v53, v54
	v_max3_f32 v0, v0, v55, v56
	v_max3_f32 v0, v0, v57, v58
	v_max3_f32 v0, v0, v59, v60
	v_max3_f32 v0, v0, v61, v62
	v_max3_f32 v0, v0, v63, v64
	v_max3_f32 v96, v34, v35, v36
	v_max3_f32 v96, v96, v37, v38
	v_max3_f32 v96, v96, v39, v40
	v_max3_f32 v96, v96, v41, v42
	v_max3_f32 v96, v96, v43, v44
	v_max3_f32 v96, v96, v45, v46
	v_max3_f32 v96, v96, v47, v48
	v_max3_f32 v96, v96, v49, v65
	v_max_f32_e32 v0, v0, v96
	v_and_b32_e32 v102, 64, v221
	v_xor_b32_e32 v96, 32, v221
	v_add_u32_e32 v102, 64, v102
	v_cmp_lt_i32_e32 vcc, v96, v102
	s_nop 1
	v_cndmask_b32_e32 v96, v221, v96, vcc
	v_lshlrev_b32_e32 v102, 2, v96
	ds_bpermute_b32 v96, v102, v0
	s_waitcnt lgkmcnt(0)
	v_max3_f32 v96, v101, v0, v96
	v_sub_f32_e32 v0, v34, v96
	v_exp_f32_e32 v34, v0
	v_sub_f32_e32 v0, v50, v96
	v_exp_f32_e32 v50, v0
	v_sub_f32_e32 v0, v35, v96
	v_exp_f32_e32 v35, v0
	v_sub_f32_e32 v0, v51, v96
	v_exp_f32_e32 v51, v0
	v_sub_f32_e32 v36, v36, v96
	v_sub_f32_e32 v52, v52, v96
	v_exp_f32_e32 v36, v36
	v_exp_f32_e32 v52, v52
	v_sub_f32_e32 v0, v101, v96
	v_add_f32_e32 v101, v34, v50
	v_add_f32_e32 v101, 0, v101
	v_add_f32_e32 v103, v35, v51
	v_add_f32_e32 v101, v103, v101
	v_add_f32_e32 v103, v36, v52
	v_sub_f32_e32 v38, v38, v96
	v_sub_f32_e32 v37, v37, v96
	v_sub_f32_e32 v53, v53, v96
	v_add_f32_e32 v103, v103, v101
	v_exp_f32_e32 v101, v38
	v_sub_f32_e32 v38, v54, v96
	v_exp_f32_e32 v37, v37
	v_exp_f32_e32 v53, v53
	v_exp_f32_e32 v54, v38
	v_sub_f32_e32 v38, v39, v96
	v_exp_f32_e32 v39, v38
	v_sub_f32_e32 v38, v55, v96
	v_exp_f32_e32 v55, v38
	v_sub_f32_e32 v40, v40, v96
	v_sub_f32_e32 v56, v56, v96
	v_exp_f32_e32 v40, v40
	v_exp_f32_e32 v56, v56
	v_sub_f32_e32 v41, v41, v96
	v_sub_f32_e32 v57, v57, v96
	v_add_f32_e32 v104, v37, v53
	v_exp_f32_e32 v41, v41
	v_exp_f32_e32 v57, v57
	v_sub_f32_e32 v42, v42, v96
	v_sub_f32_e32 v58, v58, v96
	v_add_f32_e32 v38, v104, v103
	v_add_f32_e32 v103, v101, v54
	v_exp_f32_e32 v42, v42
	v_exp_f32_e32 v58, v58
	v_sub_f32_e32 v43, v43, v96
	v_sub_f32_e32 v59, v59, v96
	v_add_f32_e32 v38, v103, v38
	v_add_f32_e32 v103, v39, v55
	v_exp_f32_e32 v43, v43
	v_exp_f32_e32 v59, v59
	v_sub_f32_e32 v44, v44, v96
	v_sub_f32_e32 v60, v60, v96
	v_add_f32_e32 v38, v103, v38
	v_add_f32_e32 v103, v40, v56
	v_exp_f32_e32 v44, v44
	v_exp_f32_e32 v60, v60
	v_sub_f32_e32 v45, v45, v96
	v_sub_f32_e32 v61, v61, v96
	v_add_f32_e32 v38, v103, v38
	v_add_f32_e32 v103, v41, v57
	v_exp_f32_e32 v45, v45
	v_exp_f32_e32 v61, v61
	v_sub_f32_e32 v46, v46, v96
	v_sub_f32_e32 v62, v62, v96
	v_add_f32_e32 v38, v103, v38
	v_add_f32_e32 v103, v42, v58
	v_exp_f32_e32 v46, v46
	v_exp_f32_e32 v62, v62
	v_sub_f32_e32 v47, v47, v96
	v_sub_f32_e32 v63, v63, v96
	v_add_f32_e32 v38, v103, v38
	v_add_f32_e32 v103, v43, v59
	v_exp_f32_e32 v47, v47
	v_exp_f32_e32 v63, v63
	v_sub_f32_e32 v48, v48, v96
	v_sub_f32_e32 v64, v64, v96
	v_add_f32_e32 v38, v103, v38
	v_add_f32_e32 v103, v44, v60
	v_exp_f32_e32 v48, v48
	v_exp_f32_e32 v64, v64
	v_sub_f32_e32 v49, v49, v96
	v_sub_f32_e32 v65, v65, v96
	v_add_f32_e32 v38, v103, v38
	v_add_f32_e32 v103, v45, v61
	v_exp_f32_e32 v49, v49
	v_exp_f32_e32 v65, v65
	v_add_f32_e32 v38, v103, v38
	v_add_f32_e32 v103, v46, v62
	v_add_f32_e32 v38, v103, v38
	v_add_f32_e32 v103, v47, v63
	v_add_f32_e32 v38, v103, v38
	v_add_f32_e32 v103, v48, v64
	v_add_f32_e32 v38, v103, v38
	v_add_f32_e32 v103, v49, v65
	v_add_f32_e32 v38, v103, v38
	v_exp_f32_e32 v0, v0
	ds_bpermute_b32 v102, v102, v38
	v_cmp_neq_f32_e32 vcc, 1.0, v0
	s_cbranch_vccz .LBB0_371
	v_pk_mul_f32 v[32:33], v[32:33], v[0:1] op_sel_hi:[1,0]
	v_pk_mul_f32 v[30:31], v[30:31], v[0:1] op_sel_hi:[1,0]
	v_pk_mul_f32 v[28:29], v[28:29], v[0:1] op_sel_hi:[1,0]
	v_pk_mul_f32 v[26:27], v[26:27], v[0:1] op_sel_hi:[1,0]
	v_pk_mul_f32 v[24:25], v[24:25], v[0:1] op_sel_hi:[1,0]
	v_pk_mul_f32 v[22:23], v[22:23], v[0:1] op_sel_hi:[1,0]
	v_pk_mul_f32 v[20:21], v[20:21], v[0:1] op_sel_hi:[1,0]
	v_pk_mul_f32 v[18:19], v[18:19], v[0:1] op_sel_hi:[1,0]
	v_pk_mul_f32 v[16:17], v[16:17], v[0:1] op_sel_hi:[1,0]
	v_pk_mul_f32 v[14:15], v[14:15], v[0:1] op_sel_hi:[1,0]
	v_pk_mul_f32 v[12:13], v[12:13], v[0:1] op_sel_hi:[1,0]
	v_pk_mul_f32 v[10:11], v[10:11], v[0:1] op_sel_hi:[1,0]
	v_pk_mul_f32 v[8:9], v[8:9], v[0:1] op_sel_hi:[1,0]
	v_pk_mul_f32 v[6:7], v[6:7], v[0:1] op_sel_hi:[1,0]
	v_pk_mul_f32 v[4:5], v[4:5], v[0:1] op_sel_hi:[1,0]
	v_pk_mul_f32 v[2:3], v[2:3], v[0:1] op_sel_hi:[1,0]

.LBB0_405:
	v_max3_f32 v101, v50, v51, v52
	v_max3_f32 v101, v101, v53, v54
	v_max3_f32 v101, v101, v55, v56
	v_max3_f32 v101, v101, v57, v58
	v_max3_f32 v101, v101, v59, v60
	v_max3_f32 v101, v101, v61, v62
	v_max3_f32 v101, v101, v63, v64
	v_max3_f32 v102, v34, v35, v36
	v_max3_f32 v102, v102, v37, v38
	v_max3_f32 v102, v102, v39, v40
	v_max3_f32 v102, v102, v41, v42
	v_max3_f32 v102, v102, v43, v44
	v_max3_f32 v102, v102, v45, v46
	v_max3_f32 v102, v102, v47, v48
	v_max3_f32 v102, v102, v49, v65
	v_max_f32_e32 v101, v101, v102
	v_and_b32_e32 v103, 64, v221
	v_xor_b32_e32 v102, 32, v221
	v_add_u32_e32 v103, 64, v103
	v_cmp_lt_i32_e32 vcc, v102, v103
	s_mov_b32 s54, s2
	s_nop 0
	v_cndmask_b32_e32 v102, v221, v102, vcc
	v_lshlrev_b32_e32 v105, 2, v102
	ds_bpermute_b32 v102, v105, v101
	s_waitcnt lgkmcnt(0)
	v_max3_f32 v101, v0, v101, v102
	v_sub_f32_e32 v34, v34, v101
	v_sub_f32_e32 v50, v50, v101
	v_exp_f32_e32 v34, v34
	v_exp_f32_e32 v50, v50
	v_sub_f32_e32 v35, v35, v101
	v_sub_f32_e32 v51, v51, v101
	v_exp_f32_e32 v35, v35
	v_exp_f32_e32 v51, v51
	v_sub_f32_e32 v36, v36, v101
	v_sub_f32_e32 v52, v52, v101
	v_exp_f32_e32 v36, v36
	v_exp_f32_e32 v52, v52
	v_add_f32_e32 v102, v34, v50
	v_sub_f32_e32 v37, v37, v101
	v_sub_f32_e32 v53, v53, v101
	v_add_f32_e32 v102, 0, v102
	v_add_f32_e32 v103, v35, v51
	v_exp_f32_e32 v37, v37
	v_exp_f32_e32 v53, v53
	v_add_f32_e32 v102, v103, v102
	v_add_f32_e32 v103, v36, v52
	v_sub_f32_e32 v38, v38, v101
	v_add_f32_e32 v104, v103, v102
	v_exp_f32_e32 v102, v38
	v_sub_f32_e32 v38, v54, v101
	v_exp_f32_e32 v54, v38
	v_sub_f32_e32 v38, v39, v101
	v_add_f32_e32 v106, v37, v53
	v_exp_f32_e32 v103, v38
	v_sub_f32_e32 v38, v55, v101
	v_sub_f32_e32 v40, v40, v101
	v_exp_f32_e32 v55, v38
	v_add_f32_e32 v38, v106, v104
	v_exp_f32_e32 v104, v40
	v_sub_f32_e32 v40, v56, v101
	v_exp_f32_e32 v56, v40
	v_add_f32_e32 v39, v102, v54
	v_add_f32_e32 v38, v39, v38
	v_add_f32_e32 v39, v103, v55
	v_sub_f32_e32 v40, v41, v101
	v_exp_f32_e32 v41, v40
	v_sub_f32_e32 v40, v57, v101
	v_add_f32_e32 v38, v39, v38
	v_add_f32_e32 v39, v104, v56
	v_exp_f32_e32 v57, v40
	v_add_f32_e32 v106, v39, v38
	v_sub_f32_e32 v38, v42, v101
	v_sub_f32_e32 v39, v58, v101
	v_exp_f32_e32 v38, v38
	v_exp_f32_e32 v39, v39
	v_add_f32_e32 v107, v41, v57
	v_sub_f32_e32 v40, v43, v101
	v_sub_f32_e32 v42, v59, v101
	v_add_f32_e32 v43, v107, v106
	v_add_f32_e32 v58, v38, v39
	v_exp_f32_e32 v40, v40
	v_exp_f32_e32 v42, v42
	v_add_f32_e32 v59, v58, v43
	v_sub_f32_e32 v43, v44, v101
	v_sub_f32_e32 v44, v60, v101
	v_exp_f32_e32 v43, v43
	v_exp_f32_e32 v44, v44
	v_add_f32_e32 v106, v40, v42
	v_sub_f32_e32 v45, v45, v101
	v_sub_f32_e32 v58, v61, v101
	v_add_f32_e32 v59, v106, v59
	v_add_f32_e32 v60, v43, v44
	v_exp_f32_e32 v45, v45
	v_exp_f32_e32 v58, v58
	v_add_f32_e32 v61, v60, v59
	v_sub_f32_e32 v46, v46, v101
	v_sub_f32_e32 v59, v62, v101
	v_exp_f32_e32 v46, v46
	v_exp_f32_e32 v59, v59
	v_add_f32_e32 v106, v45, v58
	v_sub_f32_e32 v47, v47, v101
	v_sub_f32_e32 v60, v63, v101
	v_add_f32_e32 v61, v106, v61
	v_add_f32_e32 v62, v46, v59
	v_exp_f32_e32 v47, v47
	v_exp_f32_e32 v60, v60
	v_add_f32_e32 v63, v62, v61
	v_sub_f32_e32 v48, v48, v101
	v_sub_f32_e32 v61, v64, v101
	v_exp_f32_e32 v48, v48
	v_exp_f32_e32 v61, v61
	v_sub_f32_e32 v49, v49, v101
	v_sub_f32_e32 v62, v65, v101
	v_exp_f32_e32 v49, v49
	v_exp_f32_e32 v62, v62
	v_add_f32_e32 v106, v47, v60
	v_add_f32_e32 v63, v106, v63
	v_add_f32_e32 v64, v48, v61
	v_add_f32_e32 v63, v64, v63
	v_add_f32_e32 v64, v49, v62
	v_sub_f32_e32 v0, v0, v101
	v_add_f32_e32 v63, v64, v63
	v_exp_f32_e32 v0, v0
	ds_bpermute_b32 v64, v105, v63
	v_cmp_neq_f32_e32 vcc, 1.0, v0
	s_cbranch_vccz .LBB0_407
	v_pk_mul_f32 v[16:17], v[16:17], v[0:1] op_sel_hi:[1,0]
	v_pk_mul_f32 v[14:15], v[14:15], v[0:1] op_sel_hi:[1,0]
	v_pk_mul_f32 v[12:13], v[12:13], v[0:1] op_sel_hi:[1,0]
	v_pk_mul_f32 v[10:11], v[10:11], v[0:1] op_sel_hi:[1,0]
	v_pk_mul_f32 v[8:9], v[8:9], v[0:1] op_sel_hi:[1,0]
	v_pk_mul_f32 v[6:7], v[6:7], v[0:1] op_sel_hi:[1,0]
	v_pk_mul_f32 v[4:5], v[4:5], v[0:1] op_sel_hi:[1,0]
	v_pk_mul_f32 v[2:3], v[2:3], v[0:1] op_sel_hi:[1,0]
	v_pk_mul_f32 v[32:33], v[32:33], v[0:1] op_sel_hi:[1,0]
	v_pk_mul_f32 v[30:31], v[30:31], v[0:1] op_sel_hi:[1,0]
	v_pk_mul_f32 v[28:29], v[28:29], v[0:1] op_sel_hi:[1,0]
	v_pk_mul_f32 v[26:27], v[26:27], v[0:1] op_sel_hi:[1,0]
	v_pk_mul_f32 v[24:25], v[24:25], v[0:1] op_sel_hi:[1,0]
	v_pk_mul_f32 v[22:23], v[22:23], v[0:1] op_sel_hi:[1,0]
	v_pk_mul_f32 v[20:21], v[20:21], v[0:1] op_sel_hi:[1,0]
	v_pk_mul_f32 v[18:19], v[18:19], v[0:1] op_sel_hi:[1,0]

.LBB0_474:
	s_nop 10
	v_max3_f32 v66, v34, v35, v36
	v_max3_f32 v66, v66, v37, v38
	v_max3_f32 v66, v66, v39, v40
	v_max3_f32 v66, v66, v41, v42
	v_max3_f32 v66, v66, v43, v44
	v_max3_f32 v66, v66, v45, v46
	v_max3_f32 v66, v66, v47, v48
	v_max3_f32 v67, v50, v51, v52
	v_max3_f32 v67, v67, v53, v54
	v_max3_f32 v67, v67, v55, v56
	v_max3_f32 v67, v67, v57, v58
	v_max3_f32 v67, v67, v59, v60
	v_max3_f32 v67, v67, v61, v62
	v_max3_f32 v67, v67, v63, v64
	v_max3_f32 v67, v67, v65, v49
	v_max_f32_e32 v66, v66, v67
	v_and_b32_e32 v68, 64, v221
	v_xor_b32_e32 v67, 32, v221
	v_add_u32_e32 v68, 64, v68
	v_cmp_lt_i32_e32 vcc, v67, v68
	s_nop 1
	v_cndmask_b32_e32 v67, v221, v67, vcc
	v_lshlrev_b32_e32 v70, 2, v67
	ds_bpermute_b32 v67, v70, v66
	s_waitcnt lgkmcnt(0)
	v_max3_f32 v66, v0, v66, v67
	v_sub_f32_e32 v50, v50, v66
	v_sub_f32_e32 v34, v34, v66
	v_exp_f32_e32 v50, v50
	v_exp_f32_e32 v34, v34
	v_sub_f32_e32 v51, v51, v66
	v_sub_f32_e32 v35, v35, v66
	v_exp_f32_e32 v51, v51
	v_exp_f32_e32 v35, v35
	v_sub_f32_e32 v52, v52, v66
	v_sub_f32_e32 v36, v36, v66
	v_exp_f32_e32 v52, v52
	v_exp_f32_e32 v36, v36
	v_add_f32_e32 v67, v50, v34
	v_sub_f32_e32 v53, v53, v66
	v_sub_f32_e32 v37, v37, v66
	v_add_f32_e32 v67, 0, v67
	v_add_f32_e32 v68, v51, v35
	v_exp_f32_e32 v53, v53
	v_exp_f32_e32 v37, v37
	v_add_f32_e32 v67, v68, v67
	v_add_f32_e32 v68, v52, v36
	v_sub_f32_e32 v38, v38, v66
	v_add_f32_e32 v69, v68, v67
	v_sub_f32_e32 v54, v54, v66
	v_exp_f32_e32 v67, v38
	v_sub_f32_e32 v38, v55, v66
	v_exp_f32_e32 v54, v54
	v_exp_f32_e32 v55, v38
	v_sub_f32_e32 v38, v39, v66
	v_add_f32_e32 v71, v53, v37
	v_exp_f32_e32 v68, v38
	v_sub_f32_e32 v56, v56, v66
	v_sub_f32_e32 v40, v40, v66
	v_add_f32_e32 v38, v71, v69
	v_exp_f32_e32 v56, v56
	v_exp_f32_e32 v69, v40
	v_add_f32_e32 v39, v54, v67
	v_add_f32_e32 v38, v39, v38
	v_add_f32_e32 v39, v55, v68
	v_sub_f32_e32 v40, v57, v66
	v_exp_f32_e32 v57, v40
	v_sub_f32_e32 v40, v41, v66
	v_add_f32_e32 v38, v39, v38
	v_add_f32_e32 v39, v56, v69
	v_exp_f32_e32 v41, v40
	v_add_f32_e32 v71, v39, v38
	v_sub_f32_e32 v38, v58, v66
	v_sub_f32_e32 v39, v42, v66
	v_exp_f32_e32 v38, v38
	v_exp_f32_e32 v39, v39
	v_add_f32_e32 v72, v57, v41
	v_sub_f32_e32 v40, v59, v66
	v_sub_f32_e32 v42, v43, v66
	v_add_f32_e32 v43, v72, v71
	v_add_f32_e32 v58, v38, v39
	v_exp_f32_e32 v40, v40
	v_exp_f32_e32 v42, v42
	v_add_f32_e32 v59, v58, v43
	v_sub_f32_e32 v43, v60, v66
	v_sub_f32_e32 v44, v44, v66
	v_exp_f32_e32 v43, v43
	v_exp_f32_e32 v44, v44
	v_add_f32_e32 v71, v40, v42
	v_sub_f32_e32 v58, v61, v66
	v_sub_f32_e32 v45, v45, v66
	v_add_f32_e32 v59, v71, v59
	v_add_f32_e32 v60, v43, v44
	v_exp_f32_e32 v58, v58
	v_exp_f32_e32 v45, v45
	v_add_f32_e32 v61, v60, v59
	v_sub_f32_e32 v59, v62, v66
	v_sub_f32_e32 v46, v46, v66
	v_exp_f32_e32 v59, v59
	v_exp_f32_e32 v46, v46
	v_add_f32_e32 v71, v58, v45
	v_sub_f32_e32 v60, v63, v66
	v_sub_f32_e32 v47, v47, v66
	v_add_f32_e32 v61, v71, v61
	v_add_f32_e32 v62, v59, v46
	v_exp_f32_e32 v60, v60
	v_exp_f32_e32 v47, v47
	v_add_f32_e32 v63, v62, v61
	v_sub_f32_e32 v61, v64, v66
	v_sub_f32_e32 v48, v48, v66
	v_exp_f32_e32 v61, v61
	v_exp_f32_e32 v48, v48
	v_sub_f32_e32 v62, v65, v66
	v_sub_f32_e32 v49, v49, v66
	v_exp_f32_e32 v62, v62
	v_exp_f32_e32 v49, v49
	v_add_f32_e32 v71, v60, v47
	v_add_f32_e32 v63, v71, v63
	v_add_f32_e32 v64, v61, v48
	v_add_f32_e32 v63, v64, v63
	v_add_f32_e32 v64, v62, v49
	v_sub_f32_e32 v0, v0, v66
	v_add_f32_e32 v63, v64, v63
	v_exp_f32_e32 v0, v0
	ds_bpermute_b32 v64, v70, v63
	v_cmp_neq_f32_e32 vcc, 1.0, v0
	s_cbranch_vccz .LBB0_423
	v_pk_mul_f32 v[16:17], v[16:17], v[0:1] op_sel_hi:[1,0]
	v_pk_mul_f32 v[14:15], v[14:15], v[0:1] op_sel_hi:[1,0]
	v_pk_mul_f32 v[12:13], v[12:13], v[0:1] op_sel_hi:[1,0]
	v_pk_mul_f32 v[10:11], v[10:11], v[0:1] op_sel_hi:[1,0]
	v_pk_mul_f32 v[8:9], v[8:9], v[0:1] op_sel_hi:[1,0]
	v_pk_mul_f32 v[6:7], v[6:7], v[0:1] op_sel_hi:[1,0]
	v_pk_mul_f32 v[4:5], v[4:5], v[0:1] op_sel_hi:[1,0]
	v_pk_mul_f32 v[2:3], v[2:3], v[0:1] op_sel_hi:[1,0]
	v_pk_mul_f32 v[32:33], v[32:33], v[0:1] op_sel_hi:[1,0]
	v_pk_mul_f32 v[30:31], v[30:31], v[0:1] op_sel_hi:[1,0]
	v_pk_mul_f32 v[28:29], v[28:29], v[0:1] op_sel_hi:[1,0]
	v_pk_mul_f32 v[26:27], v[26:27], v[0:1] op_sel_hi:[1,0]
	v_pk_mul_f32 v[24:25], v[24:25], v[0:1] op_sel_hi:[1,0]
	v_pk_mul_f32 v[22:23], v[22:23], v[0:1] op_sel_hi:[1,0]
	v_pk_mul_f32 v[20:21], v[20:21], v[0:1] op_sel_hi:[1,0]
	v_pk_mul_f32 v[18:19], v[18:19], v[0:1] op_sel_hi:[1,0]
	s_branch .LBB0_423

.LBB0_518:
	s_mul_i32 s0, s12, 0xa000
	v_add_u32_e32 v187, s0, v178
	s_waitcnt vmcnt(0)
	ds_read_b128 v[66:69], v187
	ds_read_b128 v[82:85], v187 offset:12288
	v_add_u32_e32 v189, s0, v180
	ds_read_b128 v[190:193], v189
	v_add_u32_e32 v194, s0, v182
	v_add_u32_e32 v195, s0, v184
	s_waitcnt lgkmcnt(0)
	v_mfma_f32_32x32x16_bf16 v[66:81], v[66:69], v[98:101], 0
	v_mfma_f32_32x32x16_bf16 v[66:81], v[190:193], v[102:105], v[66:81]
	ds_read_b128 v[190:193], v189 offset:12288
	v_mfma_f32_32x32x16_bf16 v[82:97], v[82:85], v[98:101], 0
	s_waitcnt lgkmcnt(0)
	v_mfma_f32_32x32x16_bf16 v[82:97], v[190:193], v[102:105], v[82:97]
	ds_read_b128 v[190:193], v194
	s_waitcnt lgkmcnt(0)
	v_mfma_f32_32x32x16_bf16 v[66:81], v[190:193], v[106:109], v[66:81]
	ds_read_b128 v[190:193], v194 offset:12288
	s_waitcnt lgkmcnt(0)
	v_mfma_f32_32x32x16_bf16 v[82:97], v[190:193], v[106:109], v[82:97]
	ds_read_b128 v[190:193], v195
	s_waitcnt lgkmcnt(0)
	v_mfma_f32_32x32x16_bf16 v[66:81], v[190:193], v[110:113], v[66:81]
	ds_read_b128 v[190:193], v195 offset:12288
	s_waitcnt lgkmcnt(0)
	v_mfma_f32_32x32x16_bf16 v[82:97], v[190:193], v[110:113], v[82:97]
	ds_read_b128 v[190:193], v187 offset:128
	s_waitcnt lgkmcnt(0)
	v_mfma_f32_32x32x16_bf16 v[66:81], v[190:193], v[114:117], v[66:81]
	ds_read_b128 v[190:193], v187 offset:12416
	s_waitcnt lgkmcnt(0)
	v_mfma_f32_32x32x16_bf16 v[82:97], v[190:193], v[114:117], v[82:97]
	ds_read_b128 v[190:193], v189 offset:128
	s_waitcnt lgkmcnt(0)
	v_mfma_f32_32x32x16_bf16 v[66:81], v[190:193], v[118:121], v[66:81]
	ds_read_b128 v[190:193], v189 offset:12416
	s_waitcnt lgkmcnt(0)
	v_mfma_f32_32x32x16_bf16 v[82:97], v[190:193], v[118:121], v[82:97]
	ds_read_b128 v[190:193], v194 offset:128
	s_waitcnt lgkmcnt(0)
	v_mfma_f32_32x32x16_bf16 v[66:81], v[190:193], v[122:125], v[66:81]
	ds_read_b128 v[190:193], v194 offset:12416
	s_waitcnt lgkmcnt(0)
	v_mfma_f32_32x32x16_bf16 v[82:97], v[190:193], v[122:125], v[82:97]
	ds_read_b128 v[190:193], v195 offset:128
	s_waitcnt lgkmcnt(0)
	v_mfma_f32_32x32x16_bf16 v[66:81], v[190:193], v[126:129], v[66:81]
	ds_read_b128 v[190:193], v195 offset:12416
	s_waitcnt lgkmcnt(0)
	v_mfma_f32_32x32x16_bf16 v[82:97], v[190:193], v[126:129], v[82:97]
	ds_read_b128 v[190:193], v187 offset:256
	s_waitcnt lgkmcnt(0)
	v_mfma_f32_32x32x16_bf16 v[66:81], v[190:193], v[130:133], v[66:81]
	ds_read_b128 v[190:193], v187 offset:12544
	s_waitcnt lgkmcnt(0)
	v_mfma_f32_32x32x16_bf16 v[82:97], v[190:193], v[130:133], v[82:97]
	ds_read_b128 v[190:193], v189 offset:256
	s_waitcnt lgkmcnt(0)
	v_mfma_f32_32x32x16_bf16 v[66:81], v[190:193], v[134:137], v[66:81]
	ds_read_b128 v[190:193], v189 offset:12544
	s_waitcnt lgkmcnt(0)
	v_mfma_f32_32x32x16_bf16 v[82:97], v[190:193], v[134:137], v[82:97]
	ds_read_b128 v[190:193], v194 offset:256
	s_waitcnt lgkmcnt(0)
	v_mfma_f32_32x32x16_bf16 v[66:81], v[190:193], v[138:141], v[66:81]
	ds_read_b128 v[190:193], v194 offset:12544
	s_waitcnt lgkmcnt(0)
	v_mfma_f32_32x32x16_bf16 v[82:97], v[190:193], v[138:141], v[82:97]
	ds_read_b128 v[190:193], v195 offset:12544
	s_waitcnt lgkmcnt(0)
	v_mfma_f32_32x32x16_bf16 v[82:97], v[190:193], v[142:145], v[82:97]
	ds_read_b128 v[190:193], v195 offset:256
	s_waitcnt lgkmcnt(0)
	v_mfma_f32_32x32x16_bf16 v[66:81], v[190:193], v[142:145], v[66:81]
	s_nop 8
	v_max3_f32 v187, v82, v83, v84
	v_max3_f32 v187, v187, v85, v86
	v_max3_f32 v187, v187, v87, v88
	v_max3_f32 v187, v187, v89, v90
	v_max3_f32 v187, v187, v91, v92
	v_max3_f32 v187, v187, v93, v94
	v_max3_f32 v187, v187, v95, v96
	v_max3_f32 v189, v66, v67, v68
	v_max3_f32 v189, v189, v69, v70
	v_max3_f32 v189, v189, v71, v72
	v_max3_f32 v189, v189, v73, v74
	v_max3_f32 v189, v189, v75, v76
	v_max3_f32 v189, v189, v77, v78
	v_max3_f32 v189, v189, v79, v80
	v_max3_f32 v189, v189, v81, v97
	v_max_f32_e32 v187, v187, v189
	v_and_b32_e32 v190, 64, v221
	v_xor_b32_e32 v189, 32, v221
	v_add_u32_e32 v190, 64, v190
	v_cmp_lt_i32_e32 vcc, v189, v190
	s_nop 1
	v_cndmask_b32_e32 v189, v221, v189, vcc
	v_lshlrev_b32_e32 v195, 2, v189
	ds_bpermute_b32 v189, v195, v187
	s_waitcnt lgkmcnt(0)
	v_max3_f32 v187, v188, v187, v189
	v_sub_f32_e32 v66, v66, v187
	v_exp_f32_e32 v189, v66
	v_sub_f32_e32 v66, v82, v187
	v_exp_f32_e32 v190, v66
	v_sub_f32_e32 v66, v67, v187
	v_exp_f32_e32 v67, v66
	v_sub_f32_e32 v66, v83, v187
	v_exp_f32_e32 v83, v66
	v_sub_f32_e32 v68, v68, v187
	v_sub_f32_e32 v84, v84, v187
	v_exp_f32_e32 v68, v68
	v_exp_f32_e32 v84, v84
	v_add_f32_e32 v82, v189, v190
	v_sub_f32_e32 v69, v69, v187
	v_sub_f32_e32 v85, v85, v187
	v_sub_f32_e32 v66, v188, v187
	v_add_f32_e32 v82, 0, v82
	v_add_f32_e32 v188, v67, v83
	v_exp_f32_e32 v69, v69
	v_exp_f32_e32 v85, v85
	v_add_f32_e32 v82, v188, v82
	v_add_f32_e32 v188, v68, v84
	v_sub_f32_e32 v70, v70, v187
	v_add_f32_e32 v82, v188, v82
	v_exp_f32_e32 v188, v70
	v_sub_f32_e32 v70, v86, v187
	v_exp_f32_e32 v86, v70
	v_sub_f32_e32 v70, v71, v187
	v_add_f32_e32 v192, v69, v85
	v_exp_f32_e32 v191, v70
	v_sub_f32_e32 v70, v87, v187
	v_sub_f32_e32 v72, v72, v187
	v_exp_f32_e32 v87, v70
	v_add_f32_e32 v70, v192, v82
	v_exp_f32_e32 v192, v72
	v_sub_f32_e32 v72, v88, v187
	v_exp_f32_e32 v88, v72
	v_add_f32_e32 v71, v188, v86
	v_add_f32_e32 v70, v71, v70
	v_add_f32_e32 v71, v191, v87
	v_sub_f32_e32 v72, v73, v187
	v_exp_f32_e32 v73, v72
	v_sub_f32_e32 v72, v89, v187
	v_add_f32_e32 v70, v71, v70
	v_add_f32_e32 v71, v192, v88
	v_exp_f32_e32 v89, v72
	v_add_f32_e32 v82, v71, v70
	v_sub_f32_e32 v70, v74, v187
	v_sub_f32_e32 v71, v90, v187
	v_exp_f32_e32 v70, v70
	v_exp_f32_e32 v71, v71
	v_sub_f32_e32 v72, v75, v187
	v_sub_f32_e32 v74, v91, v187
	v_exp_f32_e32 v72, v72
	v_exp_f32_e32 v75, v74
	v_sub_f32_e32 v76, v76, v187
	v_sub_f32_e32 v90, v92, v187
	v_sub_f32_e32 v78, v78, v187
	v_exp_f32_e32 v76, v76
	v_exp_f32_e32 v90, v90
	v_sub_f32_e32 v77, v77, v187
	v_sub_f32_e32 v91, v93, v187
	v_exp_f32_e32 v92, v78
	v_sub_f32_e32 v78, v94, v187
	v_add_f32_e32 v193, v73, v89
	v_exp_f32_e32 v77, v77
	v_exp_f32_e32 v91, v91
	v_exp_f32_e32 v93, v78
	v_sub_f32_e32 v78, v79, v187
	v_sub_f32_e32 v79, v80, v187
	v_add_f32_e32 v74, v193, v82
	v_add_f32_e32 v82, v70, v71
	v_exp_f32_e32 v94, v78
	v_sub_f32_e32 v78, v95, v187
	v_exp_f32_e32 v193, v79
	v_sub_f32_e32 v79, v96, v187
	v_add_f32_e32 v74, v82, v74
	v_add_f32_e32 v82, v72, v75
	v_exp_f32_e32 v95, v78
	v_exp_f32_e32 v96, v79
	v_sub_f32_e32 v79, v81, v187
	v_add_f32_e32 v74, v82, v74
	v_add_f32_e32 v82, v76, v90
	v_exp_f32_e32 v194, v79
	v_sub_f32_e32 v79, v97, v187
	v_add_f32_e32 v74, v82, v74
	v_add_f32_e32 v82, v77, v91
	v_exp_f32_e32 v97, v79
	v_add_f32_e32 v74, v82, v74
	v_add_f32_e32 v78, v92, v93
	v_add_f32_e32 v74, v78, v74
	v_add_f32_e32 v78, v94, v95
	v_add_f32_e32 v74, v78, v74
	v_add_f32_e32 v78, v193, v96
	v_add_f32_e32 v74, v78, v74
	v_add_f32_e32 v78, v194, v97
	v_add_f32_e32 v74, v78, v74
	v_exp_f32_e32 v66, v66
	ds_bpermute_b32 v78, v195, v74
	v_cmp_neq_f32_e32 vcc, 1.0, v66
	s_cbranch_vccz .LBB0_520
	v_pk_mul_f32 v[64:65], v[64:65], v[66:67] op_sel_hi:[1,0]
	v_pk_mul_f32 v[62:63], v[62:63], v[66:67] op_sel_hi:[1,0]
	v_pk_mul_f32 v[60:61], v[60:61], v[66:67] op_sel_hi:[1,0]
	v_pk_mul_f32 v[58:59], v[58:59], v[66:67] op_sel_hi:[1,0]
	v_pk_mul_f32 v[56:57], v[56:57], v[66:67] op_sel_hi:[1,0]
	v_pk_mul_f32 v[54:55], v[54:55], v[66:67] op_sel_hi:[1,0]
	v_pk_mul_f32 v[52:53], v[52:53], v[66:67] op_sel_hi:[1,0]
	v_pk_mul_f32 v[50:51], v[50:51], v[66:67] op_sel_hi:[1,0]
	v_pk_mul_f32 v[48:49], v[48:49], v[66:67] op_sel_hi:[1,0]
	v_pk_mul_f32 v[46:47], v[46:47], v[66:67] op_sel_hi:[1,0]
	v_pk_mul_f32 v[44:45], v[44:45], v[66:67] op_sel_hi:[1,0]
	v_pk_mul_f32 v[42:43], v[42:43], v[66:67] op_sel_hi:[1,0]
	v_pk_mul_f32 v[40:41], v[40:41], v[66:67] op_sel_hi:[1,0]
	v_pk_mul_f32 v[38:39], v[38:39], v[66:67] op_sel_hi:[1,0]
	v_pk_mul_f32 v[36:37], v[36:37], v[66:67] op_sel_hi:[1,0]
	v_pk_mul_f32 v[34:35], v[34:35], v[66:67] op_sel_hi:[1,0]
	v_pk_mul_f32 v[32:33], v[32:33], v[66:67] op_sel_hi:[1,0]
	v_pk_mul_f32 v[30:31], v[30:31], v[66:67] op_sel_hi:[1,0]
	v_pk_mul_f32 v[28:29], v[28:29], v[66:67] op_sel_hi:[1,0]
	v_pk_mul_f32 v[26:27], v[26:27], v[66:67] op_sel_hi:[1,0]
	v_pk_mul_f32 v[24:25], v[24:25], v[66:67] op_sel_hi:[1,0]
	v_pk_mul_f32 v[22:23], v[22:23], v[66:67] op_sel_hi:[1,0]
	v_pk_mul_f32 v[20:21], v[20:21], v[66:67] op_sel_hi:[1,0]
	v_pk_mul_f32 v[18:19], v[18:19], v[66:67] op_sel_hi:[1,0]
	v_pk_mul_f32 v[16:17], v[16:17], v[66:67] op_sel_hi:[1,0]
	v_pk_mul_f32 v[14:15], v[14:15], v[66:67] op_sel_hi:[1,0]
	v_pk_mul_f32 v[12:13], v[12:13], v[66:67] op_sel_hi:[1,0]
	v_pk_mul_f32 v[10:11], v[10:11], v[66:67] op_sel_hi:[1,0]
	v_pk_mul_f32 v[8:9], v[8:9], v[66:67] op_sel_hi:[1,0]
	v_pk_mul_f32 v[6:7], v[6:7], v[66:67] op_sel_hi:[1,0]
	v_pk_mul_f32 v[4:5], v[4:5], v[66:67] op_sel_hi:[1,0]
	v_pk_mul_f32 v[2:3], v[2:3], v[66:67] op_sel_hi:[1,0]
